# same as previous version with the poll-loop give-up caps raised from 8192 to 131072 iterations (robustness only)
# speedup vs baseline: 1.0240x; 1.0035x over previous
.Lnw_poll_n0g:
	global_load_dword v16, v14, s[12:13] sc1
	s_waitcnt vmcnt(0)
	v_readfirstlane_b32 s37, v16
	s_nop 0
	s_cmp_ge_u32 s37, s7
	s_cbranch_scc1 .Lnw_skip_n0g
	s_sleep 1
	s_add_u32 s30, s30, 1
	s_cmp_lt_u32 s30, 0x20000
	s_cbranch_scc1 .Lnw_poll_n0g

.Lgw_poll_fi:
	global_load_dword v22, v20, s[56:57] sc1
	global_load_dword v23, v21, s[56:57] sc1
	s_waitcnt vmcnt(0)
	v_readfirstlane_b32 s63, v22
	v_readfirstlane_b32 s82, v23
	s_nop 0
	s_cmp_ge_u32 s63, s59
	s_cselect_b32 s63, 1, 0
	s_cmp_ge_u32 s82, s61
	s_cselect_b32 s82, 1, 0
	s_and_b32 s63, s63, s82
	s_cmp_lg_u32 s63, 0
	s_cbranch_scc1 .Lgw_skip_fi
	s_sleep 1
	s_add_u32 s62, s62, 1
	s_cmp_lt_u32 s62, 0x20000
	s_cbranch_scc1 .Lgw_poll_fi

.Lb5_poll:
	global_load_dword v2, v0, s[6:7] sc1
	s_waitcnt vmcnt(0)
	v_readfirstlane_b32 s18, v2
	s_nop 0
	s_cmp_ge_u32 s18, s19
	s_cbranch_scc1 .Lb5_join
	s_sleep 1
	s_add_u32 s2, s2, 1
	s_cmp_lt_u32 s2, 0x20000
	s_cbranch_scc1 .Lb5_poll
	s_branch .Lb5_join
